# P9 sample_rows_gemm K loop rewritten: cooperative coalesced loads staged through padded LDS, wave w takes k-slice w of each 128-k chunk
# speedup vs baseline: 1.0059x; 1.0059x over previous
; #define MFMA32(a, b, c) __builtin_amdgcn_mfma_f32_32x32x16_bf16(a, b, c, 0, 0, 0)
; template <int WHICH> __device__ __forceinline__ void sample_rows_gemm(const Params& P, const Ctx& C) {
;     ...
;     for (int pc = C.blk; pc < 256; pc += C.nblk) {
;         const int rb = pc >> 4, cb = pc & 15;
;         const int m = NPR + rb * 32 + r32;
;         const bf16_t* wp = WT + (size_t)(cb * 64 + r32) * K + wave * KE + 8 * hi; const bf16_t* ap = ACT + (size_t)m * K + wave * KE + 8 * hi;
;         f32x16 acc0 = F16Z_, acc1 = F16Z_;
; #pragma unroll (WHICH == 0 ? 8 : 11)
;         for (int ks = 0; ks < KE / 16; ++ks) { const bf16x8 af = *(const bf16x8*)(ap + 16 * ks);
;             acc0 = MFMA32(*(const bf16x8*)(wp + 16 * ks), af, acc0); acc1 = MFMA32(*(const bf16x8*)(wp + (size_t)32 * K + 16 * ks), af, acc1); }
.LBB0_1950:
	s_and_b32 s10, s13, 0xffffffe0
	v_add_u32_e32 v0, s10, v46
	v_mad_i64_i32 v[38:39], s[10:11], v0, s15, v[34:35]
	s_lshl_b32 s10, s87, 6
	s_and_b32 s20, s10, 0x3c0
	v_or_b32_e32 v0, s20, v42
	v_mul_u32_u24_e32 v0, 0xb00, v0
	v_lshlrev_b32_e32 v36, 1, v0
	v_lshl_add_u64 v[40:41], v[32:33], 0, v[36:37]
	s_mov_b64 s[10:11], 0
	v_mov_b32_e32 v0, 0
	v_mov_b32_e32 v1, v37
	v_mov_b32_e32 v2, v37
	v_mov_b32_e32 v3, v37
	v_mov_b32_e32 v4, v37
	v_mov_b32_e32 v5, v37
	v_mov_b32_e32 v6, v37
	v_mov_b32_e32 v7, v37
	v_mov_b32_e32 v8, v37
	v_mov_b32_e32 v9, v37
	v_mov_b32_e32 v10, v37
	v_mov_b32_e32 v11, v37
	v_mov_b32_e32 v12, v37
	v_mov_b32_e32 v13, v37
	v_mov_b32_e32 v14, v37
	v_mov_b32_e32 v15, v37
	v_mov_b32_e32 v16, 0
	v_mov_b32_e32 v17, v37
	v_mov_b32_e32 v18, v37
	v_mov_b32_e32 v19, v37
	v_mov_b32_e32 v20, v37
	v_mov_b32_e32 v21, v37
	v_mov_b32_e32 v22, v37
	v_mov_b32_e32 v23, v37
	v_mov_b32_e32 v24, v37
	v_mov_b32_e32 v25, v37
	v_mov_b32_e32 v26, v37
	v_mov_b32_e32 v27, v37
	v_mov_b32_e32 v28, v37
	v_mov_b32_e32 v29, v37
	v_mov_b32_e32 v30, v37
	v_mov_b32_e32 v31, v37
	v_mbcnt_lo_u32_b32 v99, -1, 0
	v_mbcnt_hi_u32_b32 v99, -1, v99
	v_readlane_b32 vcc_hi, v254, 6
	v_lshrrev_b32_e32 v97, 4, v99
	v_and_b32_e32 v98, 15, v99
	v_mul_u32_u24_e32 v96, 5632, v97
	v_lshl_add_u32 v96, v98, 4, v96
	v_mul_u32_u24_e32 v97, 272, v97
	v_lshl_add_u32 v97, v98, 4, v97
	s_mul_i32 vcc_lo, vcc_hi, 3264
	v_add_u32_e32 v97, vcc_lo, v97
	v_and_b32_e32 v98, 31, v99
	v_mul_u32_u24_e32 v98, 272, v98
	v_lshrrev_b32_e32 v99, 5, v99
	v_lshl_add_u32 v98, v99, 4, v98
	s_lshl_b32 vcc_lo, vcc_hi, 5
	v_add_u32_e32 v98, vcc_lo, v98
	s_mul_i32 vcc_lo, vcc_hi, 12
	s_and_b32 s10, s87, 15
	s_lshl_b32 s10, s10, 6
	s_add_u32 s10, s10, vcc_lo
	s_mul_i32 s10, s10, 5632
	s_add_u32 s10, s10, 0x1500000
	s_lshr_b32 s11, s87, 4
	s_lshl_b32 s11, s11, 5
	s_add_u32 s11, s11, vcc_lo
	s_addk_i32 s11, 16320
	s_mul_i32 s11, s11, 5632
	s_add_u32 s11, s11, 0x3c300000
	s_cmp_lt_u32 vcc_lo, 64
	s_cselect_b32 s10, s10, s11
	s_add_u32 s10, s2, s10
	s_addc_u32 s11, s3, 0
	s_mul_i32 vcc_lo, vcc_hi, 12
	s_add_u32 vcc_lo, vcc_lo, 4
	s_and_b32 s98, s87, 15
	s_lshl_b32 s98, s98, 6
	s_add_u32 s98, s98, vcc_lo
	s_mul_i32 s98, s98, 5632
	s_add_u32 s98, s98, 0x1500000
	s_lshr_b32 s99, s87, 4
	s_lshl_b32 s99, s99, 5
	s_add_u32 s99, s99, vcc_lo
	s_addk_i32 s99, 16320
	s_mul_i32 s99, s99, 5632
	s_add_u32 s99, s99, 0x3c300000
	s_cmp_lt_u32 vcc_lo, 64
	s_cselect_b32 s98, s98, s99
	s_add_u32 s98, s2, s98
	s_addc_u32 s99, s3, 0
	s_mul_i32 vcc_lo, vcc_hi, 12
	s_add_u32 vcc_lo, vcc_lo, 8
	s_and_b32 s100, s87, 15
	s_lshl_b32 s100, s100, 6
	s_add_u32 s100, s100, vcc_lo
	s_mul_i32 s100, s100, 5632
	s_add_u32 s100, s100, 0x1500000
	s_lshr_b32 s101, s87, 4
	s_lshl_b32 s101, s101, 5
	s_add_u32 s101, s101, vcc_lo
	s_addk_i32 s101, 16320
	s_mul_i32 s101, s101, 5632
	s_add_u32 s101, s101, 0x3c300000
	s_cmp_lt_u32 vcc_lo, 64
	s_cselect_b32 s100, s100, s101
	s_add_u32 s100, s2, s100
	s_addc_u32 s101, s3, 0
	s_barrier
	global_load_dwordx4 v[48:51], v96, s[10:11] offset:0
	global_load_dwordx4 v[52:55], v96, s[98:99] offset:0
	global_load_dwordx4 v[56:59], v96, s[100:101] offset:0
	global_load_dwordx4 v[60:63], v96, s[10:11] offset:256
	global_load_dwordx4 v[64:67], v96, s[98:99] offset:256
	global_load_dwordx4 v[68:71], v96, s[100:101] offset:256
	global_load_dwordx4 v[72:75], v96, s[10:11] offset:512
	global_load_dwordx4 v[76:79], v96, s[98:99] offset:512
	global_load_dwordx4 v[80:83], v96, s[100:101] offset:512
	s_waitcnt vmcnt(6)
	ds_write_b128 v97, v[48:51] offset:0
	ds_write_b128 v97, v[52:55] offset:1088
	ds_write_b128 v97, v[56:59] offset:2176
	s_waitcnt lgkmcnt(0)
	s_barrier
	ds_read_b128 v[84:87], v98 offset:0
	ds_read_b128 v[92:95], v98 offset:17408
	ds_read_b128 v[88:91], v98 offset:8704
	global_load_dwordx4 v[48:51], v96, s[10:11] offset:768
	global_load_dwordx4 v[52:55], v96, s[98:99] offset:768
	global_load_dwordx4 v[56:59], v96, s[100:101] offset:768
	s_waitcnt lgkmcnt(1)
	v_mfma_f32_32x32x16_bf16 v[0:15], v[84:87], v[92:95], v[0:15]
	s_waitcnt lgkmcnt(0)
	v_mfma_f32_32x32x16_bf16 v[16:31], v[88:91], v[92:95], v[16:31]
	s_waitcnt vmcnt(6)
	ds_write_b128 v97, v[60:63] offset:26112
	ds_write_b128 v97, v[64:67] offset:27200
	ds_write_b128 v97, v[68:71] offset:28288
	s_waitcnt lgkmcnt(0)
	s_barrier
	ds_read_b128 v[84:87], v98 offset:26112
	ds_read_b128 v[92:95], v98 offset:43520
	ds_read_b128 v[88:91], v98 offset:34816
	global_load_dwordx4 v[60:63], v96, s[10:11] offset:1024
	global_load_dwordx4 v[64:67], v96, s[98:99] offset:1024
	global_load_dwordx4 v[68:71], v96, s[100:101] offset:1024
	s_waitcnt lgkmcnt(1)
	v_mfma_f32_32x32x16_bf16 v[0:15], v[84:87], v[92:95], v[0:15]
	s_waitcnt lgkmcnt(0)
	v_mfma_f32_32x32x16_bf16 v[16:31], v[88:91], v[92:95], v[16:31]
	s_waitcnt vmcnt(6)
	ds_write_b128 v97, v[72:75] offset:0
	ds_write_b128 v97, v[76:79] offset:1088
	ds_write_b128 v97, v[80:83] offset:2176
	s_waitcnt lgkmcnt(0)
	s_barrier
	ds_read_b128 v[84:87], v98 offset:0
	ds_read_b128 v[92:95], v98 offset:17408
	ds_read_b128 v[88:91], v98 offset:8704
	global_load_dwordx4 v[72:75], v96, s[10:11] offset:1280
	global_load_dwordx4 v[76:79], v96, s[98:99] offset:1280
	global_load_dwordx4 v[80:83], v96, s[100:101] offset:1280
	s_waitcnt lgkmcnt(1)
	v_mfma_f32_32x32x16_bf16 v[0:15], v[84:87], v[92:95], v[0:15]
	s_waitcnt lgkmcnt(0)
	v_mfma_f32_32x32x16_bf16 v[16:31], v[88:91], v[92:95], v[16:31]
	s_waitcnt vmcnt(6)
	ds_write_b128 v97, v[48:51] offset:26112
	ds_write_b128 v97, v[52:55] offset:27200
	ds_write_b128 v97, v[56:59] offset:28288
	s_waitcnt lgkmcnt(0)
	s_barrier
; #define MFMA32(a, b, c) __builtin_amdgcn_mfma_f32_32x32x16_bf16(a, b, c, 0, 0, 0)
; template <int WHICH> __device__ __forceinline__ void sample_rows_gemm(const Params& P, const Ctx& C) {
;     ...
;     for (int pc = C.blk; pc < 256; pc += C.nblk) {
;         const int rb = pc >> 4, cb = pc & 15;
;         const int m = NPR + rb * 32 + r32;
;         const bf16_t* wp = WT + (size_t)(cb * 64 + r32) * K + wave * KE + 8 * hi; const bf16_t* ap = ACT + (size_t)m * K + wave * KE + 8 * hi;
;         f32x16 acc0 = F16Z_, acc1 = F16Z_;
; #pragma unroll (WHICH == 0 ? 8 : 11)
;         for (int ks = 0; ks < KE / 16; ++ks) { const bf16x8 af = *(const bf16x8*)(ap + 16 * ks);
;             acc0 = MFMA32(*(const bf16x8*)(wp + 16 * ks), af, acc0); acc1 = MFMA32(*(const bf16x8*)(wp + (size_t)32 * K + 16 * ks), af, acc1); }
	ds_read_b128 v[84:87], v98 offset:26112
	ds_read_b128 v[92:95], v98 offset:43520
	ds_read_b128 v[88:91], v98 offset:34816
	global_load_dwordx4 v[48:51], v96, s[10:11] offset:1536
	global_load_dwordx4 v[52:55], v96, s[98:99] offset:1536
	global_load_dwordx4 v[56:59], v96, s[100:101] offset:1536
	s_waitcnt lgkmcnt(1)
	v_mfma_f32_32x32x16_bf16 v[0:15], v[84:87], v[92:95], v[0:15]
	s_waitcnt lgkmcnt(0)
	v_mfma_f32_32x32x16_bf16 v[16:31], v[88:91], v[92:95], v[16:31]
	s_waitcnt vmcnt(6)
	ds_write_b128 v97, v[60:63] offset:0
	ds_write_b128 v97, v[64:67] offset:1088
	ds_write_b128 v97, v[68:71] offset:2176
	s_waitcnt lgkmcnt(0)
	s_barrier
	ds_read_b128 v[84:87], v98 offset:0
	ds_read_b128 v[92:95], v98 offset:17408
	ds_read_b128 v[88:91], v98 offset:8704
	global_load_dwordx4 v[60:63], v96, s[10:11] offset:1792
	global_load_dwordx4 v[64:67], v96, s[98:99] offset:1792
	global_load_dwordx4 v[68:71], v96, s[100:101] offset:1792
	s_waitcnt lgkmcnt(1)
	v_mfma_f32_32x32x16_bf16 v[0:15], v[84:87], v[92:95], v[0:15]
	s_waitcnt lgkmcnt(0)
	v_mfma_f32_32x32x16_bf16 v[16:31], v[88:91], v[92:95], v[16:31]
	s_waitcnt vmcnt(6)
	ds_write_b128 v97, v[72:75] offset:26112
	ds_write_b128 v97, v[76:79] offset:27200
	ds_write_b128 v97, v[80:83] offset:28288
	s_waitcnt lgkmcnt(0)
	s_barrier
	ds_read_b128 v[84:87], v98 offset:26112
	ds_read_b128 v[92:95], v98 offset:43520
	ds_read_b128 v[88:91], v98 offset:34816
	global_load_dwordx4 v[72:75], v96, s[10:11] offset:2048
	global_load_dwordx4 v[76:79], v96, s[98:99] offset:2048
	global_load_dwordx4 v[80:83], v96, s[100:101] offset:2048
	s_waitcnt lgkmcnt(1)
	v_mfma_f32_32x32x16_bf16 v[0:15], v[84:87], v[92:95], v[0:15]
	s_waitcnt lgkmcnt(0)
	v_mfma_f32_32x32x16_bf16 v[16:31], v[88:91], v[92:95], v[16:31]
	s_waitcnt vmcnt(6)
	ds_write_b128 v97, v[48:51] offset:0
	ds_write_b128 v97, v[52:55] offset:1088
	ds_write_b128 v97, v[56:59] offset:2176
	s_waitcnt lgkmcnt(0)
	s_barrier
	ds_read_b128 v[84:87], v98 offset:0
	ds_read_b128 v[92:95], v98 offset:17408
	ds_read_b128 v[88:91], v98 offset:8704
	global_load_dwordx4 v[48:51], v96, s[10:11] offset:2304
	global_load_dwordx4 v[52:55], v96, s[98:99] offset:2304
	global_load_dwordx4 v[56:59], v96, s[100:101] offset:2304
	s_waitcnt lgkmcnt(1)
	v_mfma_f32_32x32x16_bf16 v[0:15], v[84:87], v[92:95], v[0:15]
	s_waitcnt lgkmcnt(0)
	v_mfma_f32_32x32x16_bf16 v[16:31], v[88:91], v[92:95], v[16:31]
	s_waitcnt vmcnt(6)
	ds_write_b128 v97, v[60:63] offset:26112
	ds_write_b128 v97, v[64:67] offset:27200
	ds_write_b128 v97, v[68:71] offset:28288
	s_waitcnt lgkmcnt(0)
	s_barrier
	ds_read_b128 v[84:87], v98 offset:26112
	ds_read_b128 v[92:95], v98 offset:43520
	ds_read_b128 v[88:91], v98 offset:34816
	global_load_dwordx4 v[60:63], v96, s[10:11] offset:2560
	global_load_dwordx4 v[64:67], v96, s[98:99] offset:2560
	global_load_dwordx4 v[68:71], v96, s[100:101] offset:2560
	s_waitcnt lgkmcnt(1)
	v_mfma_f32_32x32x16_bf16 v[0:15], v[84:87], v[92:95], v[0:15]
	s_waitcnt lgkmcnt(0)
	v_mfma_f32_32x32x16_bf16 v[16:31], v[88:91], v[92:95], v[16:31]
	s_waitcnt vmcnt(6)
	ds_write_b128 v97, v[72:75] offset:0
	ds_write_b128 v97, v[76:79] offset:1088
	ds_write_b128 v97, v[80:83] offset:2176
	s_waitcnt lgkmcnt(0)
	s_barrier
	ds_read_b128 v[84:87], v98 offset:0
	ds_read_b128 v[92:95], v98 offset:17408
	ds_read_b128 v[88:91], v98 offset:8704
	global_load_dwordx4 v[72:75], v96, s[10:11] offset:2816
	global_load_dwordx4 v[76:79], v96, s[98:99] offset:2816
	global_load_dwordx4 v[80:83], v96, s[100:101] offset:2816
	s_waitcnt lgkmcnt(1)
	v_mfma_f32_32x32x16_bf16 v[0:15], v[84:87], v[92:95], v[0:15]
	s_waitcnt lgkmcnt(0)
	v_mfma_f32_32x32x16_bf16 v[16:31], v[88:91], v[92:95], v[16:31]
	s_waitcnt vmcnt(6)
	ds_write_b128 v97, v[48:51] offset:26112
	ds_write_b128 v97, v[52:55] offset:27200
	ds_write_b128 v97, v[56:59] offset:28288
	s_waitcnt lgkmcnt(0)
	s_barrier
	ds_read_b128 v[84:87], v98 offset:26112
	ds_read_b128 v[92:95], v98 offset:43520
	ds_read_b128 v[88:91], v98 offset:34816
	global_load_dwordx4 v[48:51], v96, s[10:11] offset:3072
	global_load_dwordx4 v[52:55], v96, s[98:99] offset:3072
	global_load_dwordx4 v[56:59], v96, s[100:101] offset:3072
	s_waitcnt lgkmcnt(1)
	v_mfma_f32_32x32x16_bf16 v[0:15], v[84:87], v[92:95], v[0:15]
	s_waitcnt lgkmcnt(0)
	v_mfma_f32_32x32x16_bf16 v[16:31], v[88:91], v[92:95], v[16:31]
	s_waitcnt vmcnt(6)
	ds_write_b128 v97, v[60:63] offset:0
	ds_write_b128 v97, v[64:67] offset:1088
	ds_write_b128 v97, v[68:71] offset:2176
	s_waitcnt lgkmcnt(0)
	s_barrier
	ds_read_b128 v[84:87], v98 offset:0
	ds_read_b128 v[92:95], v98 offset:17408
	ds_read_b128 v[88:91], v98 offset:8704
	global_load_dwordx4 v[60:63], v96, s[10:11] offset:3328
	global_load_dwordx4 v[64:67], v96, s[98:99] offset:3328
	global_load_dwordx4 v[68:71], v96, s[100:101] offset:3328
	s_waitcnt lgkmcnt(1)
	v_mfma_f32_32x32x16_bf16 v[0:15], v[84:87], v[92:95], v[0:15]
	s_waitcnt lgkmcnt(0)
	v_mfma_f32_32x32x16_bf16 v[16:31], v[88:91], v[92:95], v[16:31]
	s_waitcnt vmcnt(6)
	ds_write_b128 v97, v[72:75] offset:26112
	ds_write_b128 v97, v[76:79] offset:27200
	ds_write_b128 v97, v[80:83] offset:28288
	s_waitcnt lgkmcnt(0)
	s_barrier
	ds_read_b128 v[84:87], v98 offset:26112
	ds_read_b128 v[92:95], v98 offset:43520
	ds_read_b128 v[88:91], v98 offset:34816
	global_load_dwordx4 v[72:75], v96, s[10:11] offset:3584
	global_load_dwordx4 v[76:79], v96, s[98:99] offset:3584
	global_load_dwordx4 v[80:83], v96, s[100:101] offset:3584
	s_waitcnt lgkmcnt(1)
	v_mfma_f32_32x32x16_bf16 v[0:15], v[84:87], v[92:95], v[0:15]
	s_waitcnt lgkmcnt(0)
	v_mfma_f32_32x32x16_bf16 v[16:31], v[88:91], v[92:95], v[16:31]
	s_waitcnt vmcnt(6)
	ds_write_b128 v97, v[48:51] offset:0
	ds_write_b128 v97, v[52:55] offset:1088
	ds_write_b128 v97, v[56:59] offset:2176
	s_waitcnt lgkmcnt(0)
	s_barrier
; #define MFMA32(a, b, c) __builtin_amdgcn_mfma_f32_32x32x16_bf16(a, b, c, 0, 0, 0)
; template <int WHICH> __device__ __forceinline__ void sample_rows_gemm(const Params& P, const Ctx& C) {
;     ...
;     for (int pc = C.blk; pc < 256; pc += C.nblk) {
;         const int rb = pc >> 4, cb = pc & 15;
;         const int m = NPR + rb * 32 + r32;
;         const bf16_t* wp = WT + (size_t)(cb * 64 + r32) * K + wave * KE + 8 * hi; const bf16_t* ap = ACT + (size_t)m * K + wave * KE + 8 * hi;
;         f32x16 acc0 = F16Z_, acc1 = F16Z_;
; #pragma unroll (WHICH == 0 ? 8 : 11)
;         for (int ks = 0; ks < KE / 16; ++ks) { const bf16x8 af = *(const bf16x8*)(ap + 16 * ks);
;             acc0 = MFMA32(*(const bf16x8*)(wp + 16 * ks), af, acc0); acc1 = MFMA32(*(const bf16x8*)(wp + (size_t)32 * K + 16 * ks), af, acc1); }
	ds_read_b128 v[84:87], v98 offset:0
	ds_read_b128 v[92:95], v98 offset:17408
	ds_read_b128 v[88:91], v98 offset:8704
	global_load_dwordx4 v[48:51], v96, s[10:11] offset:3840
	global_load_dwordx4 v[52:55], v96, s[98:99] offset:3840
	global_load_dwordx4 v[56:59], v96, s[100:101] offset:3840
	s_waitcnt lgkmcnt(1)
	v_mfma_f32_32x32x16_bf16 v[0:15], v[84:87], v[92:95], v[0:15]
	s_waitcnt lgkmcnt(0)
	v_mfma_f32_32x32x16_bf16 v[16:31], v[88:91], v[92:95], v[16:31]
	s_waitcnt vmcnt(6)
	ds_write_b128 v97, v[60:63] offset:26112
	ds_write_b128 v97, v[64:67] offset:27200
	ds_write_b128 v97, v[68:71] offset:28288
	s_waitcnt lgkmcnt(0)
	s_barrier
	ds_read_b128 v[84:87], v98 offset:26112
	ds_read_b128 v[92:95], v98 offset:43520
	ds_read_b128 v[88:91], v98 offset:34816
	v_add_u32_e32 v96, 0x1000, v96
	global_load_dwordx4 v[60:63], v96, s[10:11] offset:0
	global_load_dwordx4 v[64:67], v96, s[98:99] offset:0
	global_load_dwordx4 v[68:71], v96, s[100:101] offset:0
	s_waitcnt lgkmcnt(1)
	v_mfma_f32_32x32x16_bf16 v[0:15], v[84:87], v[92:95], v[0:15]
	s_waitcnt lgkmcnt(0)
	v_mfma_f32_32x32x16_bf16 v[16:31], v[88:91], v[92:95], v[16:31]
	s_waitcnt vmcnt(6)
	ds_write_b128 v97, v[72:75] offset:0
	ds_write_b128 v97, v[76:79] offset:1088
	ds_write_b128 v97, v[80:83] offset:2176
	s_waitcnt lgkmcnt(0)
	s_barrier
	ds_read_b128 v[84:87], v98 offset:0
	ds_read_b128 v[92:95], v98 offset:17408
	ds_read_b128 v[88:91], v98 offset:8704
	global_load_dwordx4 v[72:75], v96, s[10:11] offset:256
	global_load_dwordx4 v[76:79], v96, s[98:99] offset:256
	global_load_dwordx4 v[80:83], v96, s[100:101] offset:256
	s_waitcnt lgkmcnt(1)
	v_mfma_f32_32x32x16_bf16 v[0:15], v[84:87], v[92:95], v[0:15]
	s_waitcnt lgkmcnt(0)
	v_mfma_f32_32x32x16_bf16 v[16:31], v[88:91], v[92:95], v[16:31]
	s_waitcnt vmcnt(6)
	ds_write_b128 v97, v[48:51] offset:26112
	ds_write_b128 v97, v[52:55] offset:27200
	ds_write_b128 v97, v[56:59] offset:28288
	s_waitcnt lgkmcnt(0)
	s_barrier
	ds_read_b128 v[84:87], v98 offset:26112
	ds_read_b128 v[92:95], v98 offset:43520
	ds_read_b128 v[88:91], v98 offset:34816
	global_load_dwordx4 v[48:51], v96, s[10:11] offset:512
	global_load_dwordx4 v[52:55], v96, s[98:99] offset:512
	global_load_dwordx4 v[56:59], v96, s[100:101] offset:512
	s_waitcnt lgkmcnt(1)
	v_mfma_f32_32x32x16_bf16 v[0:15], v[84:87], v[92:95], v[0:15]
	s_waitcnt lgkmcnt(0)
	v_mfma_f32_32x32x16_bf16 v[16:31], v[88:91], v[92:95], v[16:31]
	s_waitcnt vmcnt(6)
	ds_write_b128 v97, v[60:63] offset:0
	ds_write_b128 v97, v[64:67] offset:1088
	ds_write_b128 v97, v[68:71] offset:2176
	s_waitcnt lgkmcnt(0)
	s_barrier
	ds_read_b128 v[84:87], v98 offset:0
	ds_read_b128 v[92:95], v98 offset:17408
	ds_read_b128 v[88:91], v98 offset:8704
	global_load_dwordx4 v[60:63], v96, s[10:11] offset:768
	global_load_dwordx4 v[64:67], v96, s[98:99] offset:768
	global_load_dwordx4 v[68:71], v96, s[100:101] offset:768
	s_waitcnt lgkmcnt(1)
	v_mfma_f32_32x32x16_bf16 v[0:15], v[84:87], v[92:95], v[0:15]
	s_waitcnt lgkmcnt(0)
	v_mfma_f32_32x32x16_bf16 v[16:31], v[88:91], v[92:95], v[16:31]
	s_waitcnt vmcnt(6)
	ds_write_b128 v97, v[72:75] offset:26112
	ds_write_b128 v97, v[76:79] offset:27200
	ds_write_b128 v97, v[80:83] offset:28288
	s_waitcnt lgkmcnt(0)
	s_barrier
	ds_read_b128 v[84:87], v98 offset:26112
	ds_read_b128 v[92:95], v98 offset:43520
	ds_read_b128 v[88:91], v98 offset:34816
	global_load_dwordx4 v[72:75], v96, s[10:11] offset:1024
	global_load_dwordx4 v[76:79], v96, s[98:99] offset:1024
	global_load_dwordx4 v[80:83], v96, s[100:101] offset:1024
	s_waitcnt lgkmcnt(1)
	v_mfma_f32_32x32x16_bf16 v[0:15], v[84:87], v[92:95], v[0:15]
	s_waitcnt lgkmcnt(0)
	v_mfma_f32_32x32x16_bf16 v[16:31], v[88:91], v[92:95], v[16:31]
	s_waitcnt vmcnt(6)
	ds_write_b128 v97, v[48:51] offset:0
	ds_write_b128 v97, v[52:55] offset:1088
	ds_write_b128 v97, v[56:59] offset:2176
	s_waitcnt lgkmcnt(0)
	s_barrier
	ds_read_b128 v[84:87], v98 offset:0
	ds_read_b128 v[92:95], v98 offset:17408
	ds_read_b128 v[88:91], v98 offset:8704
	global_load_dwordx4 v[48:51], v96, s[10:11] offset:1280
	global_load_dwordx4 v[52:55], v96, s[98:99] offset:1280
	global_load_dwordx4 v[56:59], v96, s[100:101] offset:1280
	s_waitcnt lgkmcnt(1)
	v_mfma_f32_32x32x16_bf16 v[0:15], v[84:87], v[92:95], v[0:15]
	s_waitcnt lgkmcnt(0)
	v_mfma_f32_32x32x16_bf16 v[16:31], v[88:91], v[92:95], v[16:31]
	s_waitcnt vmcnt(6)
	ds_write_b128 v97, v[60:63] offset:26112
	ds_write_b128 v97, v[64:67] offset:27200
	ds_write_b128 v97, v[68:71] offset:28288
	s_waitcnt lgkmcnt(0)
	s_barrier
	ds_read_b128 v[84:87], v98 offset:26112
	ds_read_b128 v[92:95], v98 offset:43520
	ds_read_b128 v[88:91], v98 offset:34816
	s_waitcnt lgkmcnt(1)
	v_mfma_f32_32x32x16_bf16 v[0:15], v[84:87], v[92:95], v[0:15]
	s_waitcnt lgkmcnt(0)
	v_mfma_f32_32x32x16_bf16 v[16:31], v[88:91], v[92:95], v[16:31]
	s_waitcnt vmcnt(3)
	ds_write_b128 v97, v[72:75] offset:0
	ds_write_b128 v97, v[76:79] offset:1088
	ds_write_b128 v97, v[80:83] offset:2176
	s_waitcnt lgkmcnt(0)
	s_barrier
	ds_read_b128 v[84:87], v98 offset:0
	ds_read_b128 v[92:95], v98 offset:17408
	ds_read_b128 v[88:91], v98 offset:8704
	s_waitcnt lgkmcnt(1)
	v_mfma_f32_32x32x16_bf16 v[0:15], v[84:87], v[92:95], v[0:15]
	s_waitcnt lgkmcnt(0)
	v_mfma_f32_32x32x16_bf16 v[16:31], v[88:91], v[92:95], v[16:31]
	s_waitcnt vmcnt(0)
	ds_write_b128 v97, v[48:51] offset:26112
	ds_write_b128 v97, v[52:55] offset:27200
	ds_write_b128 v97, v[56:59] offset:28288
	s_waitcnt lgkmcnt(0)
	s_barrier
	ds_read_b128 v[84:87], v98 offset:26112
	ds_read_b128 v[92:95], v98 offset:43520
	ds_read_b128 v[88:91], v98 offset:34816
	s_waitcnt lgkmcnt(1)
	v_mfma_f32_32x32x16_bf16 v[0:15], v[84:87], v[92:95], v[0:15]
	s_waitcnt lgkmcnt(0)
	v_mfma_f32_32x32x16_bf16 v[16:31], v[88:91], v[92:95], v[16:31]
	s_nop 1
	s_and_b64 vcc, exec, s[4:5]
	s_waitcnt lgkmcnt(0)
	s_barrier
; template <int WHICH> __device__ __forceinline__ void sample_rows_gemm(const Params& P, const Ctx& C) {
;     ...
;         __syncthreads();
; #pragma unroll
;         for (int r = 0; r < 16; ++r) { R[((wave * 2 + 0) * 16 + r) * 64 + lane] = acc0[r]; R[((wave * 2 + 1) * 16 + r) * 64 + lane] = acc1[r]; }
;         __syncthreads();
;         if (wave < 2) { const int nb = wave; f32x16 acc;
; #pragma unroll
;             for (int r = 0; r < 16; ++r) { float s = R[((0 * 2 + nb) * 16 + r) * 64 + lane];
; #pragma unroll
;                 for (int w8 = 1; w8 < 8; ++w8) s += R[((w8 * 2 + nb) * 16 + r) * 64 + lane];
;                 acc[r] = s; }
;             const float* MOD = (const float*)(ws + WS_MOD) + (size_t)pg8::mod_row(m) * 6144 + (WHICH == 0 ? 2048 : 5120);
;             const float* res = (WHICH == 0) ? P.in[1] + (size_t)(m - NPR) * DM : (const float*)(ws + WS_X1) + (size_t)m * DM;
;             float* dst = (WHICH == 0) ? (float*)(ws + WS_X1) + (size_t)m * DM : P.out + (size_t)m * DM;
; #pragma unroll
;             for (int rq = 0; rq < 4; ++rq) { const int c0 = cb * 64 + nb * 32 + 8 * rq + 4 * hi;
;                 const f32x4 a = {acc[4 * rq], acc[4 * rq + 1], acc[4 * rq + 2], acc[4 * rq + 3]};
;                 *(f32x4*)(dst + c0) = *(const f32x4*)(res + c0) + *(const f32x4*)(MOD + c0) * a; }
	s_nop 5
	ds_write2st64_b32 v45, v0, v1 offset1:1
	s_nop 0
	ds_write2st64_b32 v45, v16, v17 offset0:16 offset1:17
	ds_write2st64_b32 v45, v2, v3 offset0:2 offset1:3
	ds_write2st64_b32 v45, v18, v19 offset0:18 offset1:19
	ds_write2st64_b32 v45, v4, v5 offset0:4 offset1:5
	ds_write2st64_b32 v45, v20, v21 offset0:20 offset1:21
	ds_write2st64_b32 v45, v6, v7 offset0:6 offset1:7
	ds_write2st64_b32 v45, v22, v23 offset0:22 offset1:23
	ds_write2st64_b32 v45, v8, v9 offset0:8 offset1:9
	ds_write2st64_b32 v45, v24, v25 offset0:24 offset1:25
	ds_write2st64_b32 v45, v10, v11 offset0:10 offset1:11
	ds_write2st64_b32 v45, v26, v27 offset0:26 offset1:27
	ds_write2st64_b32 v45, v12, v13 offset0:12 offset1:13
	ds_write2st64_b32 v45, v28, v29 offset0:28 offset1:29
	ds_write2st64_b32 v45, v14, v15 offset0:14 offset1:15
	ds_write2st64_b32 v45, v30, v31 offset0:30 offset1:31
	s_waitcnt lgkmcnt(0)
	s_barrier
	s_cbranch_vccz .LBB0_1949
	s_lshl_b32 s10, s87, 1
	s_andn2_b32 s10, s10, 31
	s_addk_i32 s10, 0x4000
	v_or_b32_e32 v0, s10, v42
	v_add_u32_e32 v2, 0xffffc000, v0
	s_ashr_i32 s10, s10, 13
	v_lshrrev_b32_e32 v2, 2, v2
	v_add_u32_e32 v2, 2, v2
	v_mov_b32_e32 v3, s10
	v_cmp_gt_i32_e32 vcc, s12, v0
	v_ashrrev_i32_e32 v1, 31, v0
	v_lshlrev_b64 v[8:9], 12, v[0:1]
	v_cndmask_b32_e32 v4, v2, v3, vcc
	v_mov_b64_e32 v[2:3], s[2:3]
	v_mad_i64_i32 v[2:3], s[10:11], v4, s18, v[2:3]
	v_add_u32_e32 v4, s20, v44
	v_ashrrev_i32_e32 v5, 31, v4
	v_lshlrev_b64 v[10:11], 2, v[4:5]
	v_lshl_add_u64 v[0:1], s[6:7], 0, v[8:9]
	v_lshl_add_u64 v[14:15], v[2:3], 0, v[10:11]
	v_lshl_add_u64 v[12:13], v[0:1], 0, v[10:11]
	v_add_co_u32_e32 v16, vcc, s19, v14
	v_lshl_add_u64 v[8:9], s[0:1], 0, v[8:9]
	s_nop 0
	v_addc_co_u32_e32 v17, vcc, 0, v15, vcc
	global_load_dwordx4 v[0:3], v[12:13], off
	global_load_dwordx4 v[4:7], v[16:17], off
	ds_read2st64_b32 v[16:17], v43 offset1:1
	ds_read2st64_b32 v[18:19], v43 offset0:2 offset1:3
	ds_read2st64_b32 v[20:21], v43 offset0:4 offset1:5
	ds_read2st64_b32 v[22:23], v43 offset0:6 offset1:7
	ds_read2st64_b32 v[24:25], v43 offset0:32 offset1:33
	ds_read2st64_b32 v[26:27], v43 offset0:34 offset1:35
	ds_read2st64_b32 v[28:29], v43 offset0:36 offset1:37
	ds_read2st64_b32 v[30:31], v43 offset0:38 offset1:39
	ds_read2st64_b32 v[38:39], v43 offset0:64 offset1:65
	ds_read2st64_b32 v[40:41], v43 offset0:66 offset1:67
	ds_read2st64_b32 v[48:49], v43 offset0:68 offset1:69
	ds_read2st64_b32 v[50:51], v43 offset0:70 offset1:71
	ds_read2st64_b32 v[52:53], v43 offset0:96 offset1:97
	ds_read2st64_b32 v[54:55], v43 offset0:98 offset1:99
	ds_read2st64_b32 v[56:57], v43 offset0:100 offset1:101
	ds_read2st64_b32 v[58:59], v43 offset0:102 offset1:103
	ds_read2st64_b32 v[60:61], v43 offset0:128 offset1:129
	ds_read2st64_b32 v[62:63], v43 offset0:130 offset1:131
	ds_read2st64_b32 v[64:65], v43 offset0:132 offset1:133
	ds_read2st64_b32 v[66:67], v43 offset0:134 offset1:135
	ds_read2st64_b32 v[68:69], v43 offset0:160 offset1:161
	ds_read2st64_b32 v[70:71], v43 offset0:162 offset1:163
	ds_read2st64_b32 v[72:73], v43 offset0:164 offset1:165
	ds_read2st64_b32 v[74:75], v43 offset0:166 offset1:167
	ds_read2st64_b32 v[76:77], v43 offset0:192 offset1:193
	ds_read2st64_b32 v[78:79], v43 offset0:194 offset1:195
	ds_read2st64_b32 v[80:81], v43 offset0:196 offset1:197
	ds_read2st64_b32 v[82:83], v43 offset0:198 offset1:199
	ds_read2st64_b32 v[84:85], v43 offset0:224 offset1:225
	ds_read2st64_b32 v[86:87], v43 offset0:226 offset1:227
	ds_read2st64_b32 v[88:89], v43 offset0:228 offset1:229
	ds_read2st64_b32 v[90:91], v43 offset0:230 offset1:231
	s_waitcnt lgkmcnt(14)
	v_pk_add_f32 v[16:17], v[16:17], v[24:25]
	v_pk_add_f32 v[18:19], v[18:19], v[26:27]
	v_pk_add_f32 v[16:17], v[16:17], v[38:39]
	v_pk_add_f32 v[18:19], v[18:19], v[40:41]
	v_pk_add_f32 v[16:17], v[16:17], v[52:53]
	v_pk_add_f32 v[18:19], v[18:19], v[54:55]
	v_lshl_add_u64 v[8:9], v[8:9], 0, v[10:11]
	v_pk_add_f32 v[10:11], v[16:17], v[60:61]
	v_pk_add_f32 v[16:17], v[18:19], v[62:63]
	s_waitcnt lgkmcnt(11)
	v_pk_add_f32 v[10:11], v[10:11], v[68:69]
	s_waitcnt lgkmcnt(10)
	v_pk_add_f32 v[16:17], v[16:17], v[70:71]
	s_waitcnt lgkmcnt(7)
	v_pk_add_f32 v[10:11], v[10:11], v[76:77]
	s_waitcnt lgkmcnt(6)
	v_pk_add_f32 v[16:17], v[16:17], v[78:79]
	s_waitcnt lgkmcnt(3)
	v_pk_add_f32 v[10:11], v[10:11], v[84:85]
	s_waitcnt lgkmcnt(2)
	v_pk_add_f32 v[16:17], v[16:17], v[86:87]
	v_lshl_add_u64 v[14:15], v[14:15], 0, s[8:9]
	s_waitcnt vmcnt(0)
; template <int WHICH> __device__ __forceinline__ void sample_rows_gemm(const Params& P, const Ctx& C) {
;     ...
;         if (wave < 2) { const int nb = wave; f32x16 acc;
; #pragma unroll
;             for (int r = 0; r < 16; ++r) { float s = R[((0 * 2 + nb) * 16 + r) * 64 + lane];
; #pragma unroll
;                 for (int w8 = 1; w8 < 8; ++w8) s += R[((w8 * 2 + nb) * 16 + r) * 64 + lane];
;                 acc[r] = s; }
;             const float* MOD = (const float*)(ws + WS_MOD) + (size_t)pg8::mod_row(m) * 6144 + (WHICH == 0 ? 2048 : 5120);
;             const float* res = (WHICH == 0) ? P.in[1] + (size_t)(m - NPR) * DM : (const float*)(ws + WS_X1) + (size_t)m * DM;
;             float* dst = (WHICH == 0) ? (float*)(ws + WS_X1) + (size_t)m * DM : P.out + (size_t)m * DM;
; #pragma unroll
;             for (int rq = 0; rq < 4; ++rq) { const int c0 = cb * 64 + nb * 32 + 8 * rq + 4 * hi;
;                 const f32x4 a = {acc[4 * rq], acc[4 * rq + 1], acc[4 * rq + 2], acc[4 * rq + 3]};
;                 *(f32x4*)(dst + c0) = *(const f32x4*)(res + c0) + *(const f32x4*)(MOD + c0) * a; }
	v_pk_fma_f32 v[2:3], v[16:17], v[6:7], v[2:3]
	v_pk_fma_f32 v[0:1], v[10:11], v[4:5], v[0:1]
	global_store_dwordx4 v[8:9], v[0:3], off
	global_load_dwordx4 v[0:3], v[12:13], off offset:32
	s_nop 0
	global_load_dwordx4 v[4:7], v[14:15], off offset:32
	v_pk_add_f32 v[10:11], v[20:21], v[28:29]
	v_pk_add_f32 v[16:17], v[22:23], v[30:31]
	v_pk_add_f32 v[10:11], v[10:11], v[48:49]
	v_pk_add_f32 v[16:17], v[16:17], v[50:51]
	v_pk_add_f32 v[10:11], v[10:11], v[56:57]
	v_pk_add_f32 v[16:17], v[16:17], v[58:59]
	v_pk_add_f32 v[10:11], v[10:11], v[64:65]
	v_pk_add_f32 v[16:17], v[16:17], v[66:67]
	v_pk_add_f32 v[10:11], v[10:11], v[72:73]
	v_pk_add_f32 v[16:17], v[16:17], v[74:75]
	v_pk_add_f32 v[10:11], v[10:11], v[80:81]
	v_pk_add_f32 v[16:17], v[16:17], v[82:83]
	s_waitcnt lgkmcnt(1)
	v_pk_add_f32 v[10:11], v[10:11], v[88:89]
	s_waitcnt lgkmcnt(0)
	v_pk_add_f32 v[16:17], v[16:17], v[90:91]
	s_waitcnt vmcnt(0)
	v_pk_fma_f32 v[0:1], v[10:11], v[4:5], v[0:1]
	v_pk_fma_f32 v[2:3], v[16:17], v[6:7], v[2:3]
	global_store_dwordx4 v[8:9], v[0:3], off offset:32
	global_load_dwordx4 v[0:3], v[12:13], off offset:64
	s_nop 0
	global_load_dwordx4 v[4:7], v[14:15], off offset:64
	ds_read2st64_b32 v[10:11], v43 offset0:8 offset1:9
	ds_read2st64_b32 v[16:17], v43 offset0:10 offset1:11
	ds_read2st64_b32 v[18:19], v43 offset0:12 offset1:13
	ds_read2st64_b32 v[20:21], v43 offset0:14 offset1:15
	ds_read2st64_b32 v[22:23], v43 offset0:40 offset1:41
	ds_read2st64_b32 v[24:25], v43 offset0:42 offset1:43
	ds_read2st64_b32 v[26:27], v43 offset0:44 offset1:45
	ds_read2st64_b32 v[28:29], v43 offset0:46 offset1:47
	ds_read2st64_b32 v[30:31], v43 offset0:72 offset1:73
	ds_read2st64_b32 v[38:39], v43 offset0:74 offset1:75
	ds_read2st64_b32 v[40:41], v43 offset0:76 offset1:77
	ds_read2st64_b32 v[48:49], v43 offset0:78 offset1:79
	ds_read2st64_b32 v[50:51], v43 offset0:104 offset1:105
	ds_read2st64_b32 v[52:53], v43 offset0:106 offset1:107
	ds_read2st64_b32 v[54:55], v43 offset0:108 offset1:109
	ds_read2st64_b32 v[56:57], v43 offset0:110 offset1:111
	ds_read2st64_b32 v[58:59], v43 offset0:136 offset1:137
	ds_read2st64_b32 v[60:61], v43 offset0:138 offset1:139
	ds_read2st64_b32 v[62:63], v43 offset0:140 offset1:141
	ds_read2st64_b32 v[64:65], v43 offset0:142 offset1:143
	ds_read2st64_b32 v[66:67], v43 offset0:168 offset1:169
	ds_read2st64_b32 v[68:69], v43 offset0:170 offset1:171
	ds_read2st64_b32 v[70:71], v43 offset0:172 offset1:173
	ds_read2st64_b32 v[72:73], v43 offset0:174 offset1:175
	ds_read2st64_b32 v[74:75], v43 offset0:200 offset1:201
	ds_read2st64_b32 v[76:77], v43 offset0:202 offset1:203
	ds_read2st64_b32 v[78:79], v43 offset0:204 offset1:205
	ds_read2st64_b32 v[80:81], v43 offset0:206 offset1:207
	ds_read2st64_b32 v[82:83], v43 offset0:232 offset1:233
	ds_read2st64_b32 v[84:85], v43 offset0:234 offset1:235
	ds_read2st64_b32 v[86:87], v43 offset0:236 offset1:237
	ds_read2st64_b32 v[88:89], v43 offset0:238 offset1:239
	s_waitcnt lgkmcnt(14)
	v_pk_add_f32 v[10:11], v[10:11], v[22:23]
	v_pk_add_f32 v[16:17], v[16:17], v[24:25]
	v_pk_add_f32 v[10:11], v[10:11], v[30:31]
	v_pk_add_f32 v[16:17], v[16:17], v[38:39]
	v_pk_add_f32 v[10:11], v[10:11], v[50:51]
	v_pk_add_f32 v[16:17], v[16:17], v[52:53]
	v_pk_add_f32 v[10:11], v[10:11], v[58:59]
	v_pk_add_f32 v[16:17], v[16:17], v[60:61]
	s_waitcnt lgkmcnt(11)
	v_pk_add_f32 v[10:11], v[10:11], v[66:67]
	s_waitcnt lgkmcnt(10)
	v_pk_add_f32 v[16:17], v[16:17], v[68:69]
	s_waitcnt lgkmcnt(7)
	v_pk_add_f32 v[10:11], v[10:11], v[74:75]
	s_waitcnt lgkmcnt(6)
	v_pk_add_f32 v[16:17], v[16:17], v[76:77]
	s_waitcnt lgkmcnt(3)
	v_pk_add_f32 v[10:11], v[10:11], v[82:83]
	s_waitcnt lgkmcnt(2)
	v_pk_add_f32 v[16:17], v[16:17], v[84:85]
	s_waitcnt vmcnt(0)
	v_pk_fma_f32 v[0:1], v[10:11], v[4:5], v[0:1]
	v_pk_fma_f32 v[2:3], v[16:17], v[6:7], v[2:3]
	global_store_dwordx4 v[8:9], v[0:3], off offset:64
	global_load_dwordx4 v[0:3], v[12:13], off offset:96
	s_nop 0
	global_load_dwordx4 v[4:7], v[14:15], off offset:96
	v_pk_add_f32 v[10:11], v[18:19], v[26:27]
	v_pk_add_f32 v[12:13], v[20:21], v[28:29]
	v_pk_add_f32 v[10:11], v[10:11], v[40:41]
	v_pk_add_f32 v[12:13], v[12:13], v[48:49]
	v_pk_add_f32 v[10:11], v[10:11], v[54:55]
	v_pk_add_f32 v[12:13], v[12:13], v[56:57]
	v_pk_add_f32 v[10:11], v[10:11], v[62:63]
	v_pk_add_f32 v[12:13], v[12:13], v[64:65]
	v_pk_add_f32 v[10:11], v[10:11], v[70:71]
	v_pk_add_f32 v[12:13], v[12:13], v[72:73]
	v_pk_add_f32 v[10:11], v[10:11], v[78:79]
	v_pk_add_f32 v[12:13], v[12:13], v[80:81]
	s_waitcnt lgkmcnt(1)
	v_pk_add_f32 v[10:11], v[10:11], v[86:87]
	s_waitcnt lgkmcnt(0)
	v_pk_add_f32 v[12:13], v[12:13], v[88:89]
	s_waitcnt vmcnt(0)
	v_pk_fma_f32 v[0:1], v[10:11], v[4:5], v[0:1]
	v_pk_fma_f32 v[2:3], v[12:13], v[6:7], v[2:3]
	global_store_dwordx4 v[8:9], v[0:3], off offset:96
	s_branch .LBB0_1949

; __global__ void __launch_bounds__(NWAVES * 64, 2) fwd_kernel(Params P) {
	.amdhsa_kernel _Z10fwd_kernel6Params
		.amdhsa_group_segment_fixed_size 0
		.amdhsa_private_segment_fixed_size 0
		.amdhsa_kernarg_size 544
		.amdhsa_user_sgpr_count 2
		.amdhsa_user_sgpr_dispatch_ptr 0
		.amdhsa_user_sgpr_queue_ptr 0
		.amdhsa_user_sgpr_kernarg_segment_ptr 1
		.amdhsa_user_sgpr_dispatch_id 0
		.amdhsa_user_sgpr_kernarg_preload_length 0
		.amdhsa_user_sgpr_kernarg_preload_offset 0
		.amdhsa_user_sgpr_private_segment_size 0
		.amdhsa_uses_dynamic_stack 0
		.amdhsa_enable_private_segment 0
		.amdhsa_system_sgpr_workgroup_id_x 1
		.amdhsa_system_sgpr_workgroup_id_y 0
		.amdhsa_system_sgpr_workgroup_id_z 0
		.amdhsa_system_sgpr_workgroup_info 0
		.amdhsa_system_vgpr_workitem_id 0
		.amdhsa_next_free_vgpr 256
		.amdhsa_next_free_sgpr 102
		.amdhsa_accum_offset 256
		.amdhsa_reserve_vcc 1
		.amdhsa_float_round_mode_32 0
		.amdhsa_float_round_mode_16_64 0
		.amdhsa_float_denorm_mode_32 3
		.amdhsa_float_denorm_mode_16_64 3
		.amdhsa_dx10_clamp 1
		.amdhsa_ieee_mode 1
		.amdhsa_fp16_overflow 0
		.amdhsa_tg_split 0
		.amdhsa_exception_fp_ieee_invalid_op 0
		.amdhsa_exception_fp_denorm_src 0
		.amdhsa_exception_fp_ieee_div_zero 0
		.amdhsa_exception_fp_ieee_overflow 0
		.amdhsa_exception_fp_ieee_underflow 0
		.amdhsa_exception_fp_ieee_inexact 0
		.amdhsa_exception_int_div_zero 0
	.end_amdhsa_kernel

; __global__ void __launch_bounds__(NWAVES * 64, 2) fwd_kernel(Params P) {
amdhsa.kernels:
  - .agpr_count:     0
    .args:
      - .offset:         0
        .size:           288
        .value_kind:     by_value
      - .offset:         288
        .size:           4
        .value_kind:     hidden_block_count_x
      - .offset:         292
        .size:           4
        .value_kind:     hidden_block_count_y
      - .offset:         296
        .size:           4
        .value_kind:     hidden_block_count_z
      - .offset:         300
        .size:           2
        .value_kind:     hidden_group_size_x
      - .offset:         302
        .size:           2
        .value_kind:     hidden_group_size_y
      - .offset:         304
        .size:           2
        .value_kind:     hidden_group_size_z
      - .offset:         306
        .size:           2
        .value_kind:     hidden_remainder_x
      - .offset:         308
        .size:           2
        .value_kind:     hidden_remainder_y
      - .offset:         310
        .size:           2
        .value_kind:     hidden_remainder_z
      - .offset:         328
        .size:           8
        .value_kind:     hidden_global_offset_x
      - .offset:         336
        .size:           8
        .value_kind:     hidden_global_offset_y
      - .offset:         344
        .size:           8
        .value_kind:     hidden_global_offset_z
      - .offset:         352
        .size:           2
        .value_kind:     hidden_grid_dims
      - .offset:         408
        .size:           4
        .value_kind:     hidden_dynamic_lds_size
    .group_segment_fixed_size: 0
    .kernarg_segment_align: 8
    .kernarg_segment_size: 544
    .language:       OpenCL C
    .language_version:
      - 2
      - 0
    .max_flat_workgroup_size: 512
    .name:           _Z10fwd_kernel6Params
    .private_segment_fixed_size: 0
    .sgpr_count:     108
    .sgpr_spill_count: 147
    .symbol:         _Z10fwd_kernel6Params.kd
    .uniform_work_group_size: 1
    .uses_dynamic_stack: false
    .vgpr_count:     256
    .vgpr_spill_count: 0
    .wavefront_size: 64
